# conv-layer residual epilogues: second batch of old-hb loads issued with the first (no wait on the first half's stores)
# speedup vs baseline: 1.0009x; 1.0009x over previous
.LBB0_265:
	v_lshl_or_b32 v166, s16, 8, v196
	v_lshl_add_u32 v170, s68, 8, v194
	v_ashrrev_i32_e32 v167, 31, v166
	v_lshlrev_b64 v[204:205], 1, v[166:167]
	v_ashrrev_i32_e32 v171, 31, v170
	v_lshl_add_u64 v[168:169], s[18:19], 0, v[204:205]
	v_lshlrev_b64 v[206:207], 11, v[170:171]
	v_lshl_add_u64 v[128:129], v[168:169], 0, v[206:207]
	global_load_dwordx4 v[200:203], v[128:129], off
	global_load_dwordx4 v[152:155], v[128:129], off offset:256
	v_or_b32_e32 v190, 16, v170
	v_ashrrev_i32_e32 v191, 31, v190
	v_or_b32_e32 v186, 32, v170
	v_lshlrev_b64 v[192:193], 11, v[190:191]
	v_ashrrev_i32_e32 v187, 31, v186
	v_or_b32_e32 v172, 48, v170
	v_lshl_add_u64 v[128:129], v[168:169], 0, v[192:193]
	v_lshlrev_b64 v[188:189], 11, v[186:187]
	v_ashrrev_i32_e32 v173, 31, v172
	global_load_dwordx4 v[148:151], v[128:129], off
	global_load_dwordx4 v[144:147], v[128:129], off offset:256
	v_lshl_add_u64 v[128:129], v[168:169], 0, v[188:189]
	v_lshlrev_b64 v[174:175], 11, v[172:173]
	global_load_dwordx4 v[140:143], v[128:129], off
	global_load_dwordx4 v[136:139], v[128:129], off offset:256
	v_lshl_add_u64 v[128:129], v[168:169], 0, v[174:175]
	global_load_dwordx4 v[132:135], v[128:129], off
	s_nop 0
	global_load_dwordx4 v[128:131], v[128:129], off offset:256
	v_add_u32_e32 v216, 0x80, v170
	v_ashrrev_i32_e32 v217, 31, v216
	v_lshlrev_b64 v[216:217], 11, v[216:217]
	v_lshl_add_u64 v[216:217], v[168:169], 0, v[216:217]
	global_load_dwordx4 v[212:215], v[216:217], off
	global_load_dwordx4 v[222:225], v[216:217], off offset:256
	v_add_u32_e32 v216, 0x90, v170
	v_ashrrev_i32_e32 v217, 31, v216
	v_lshlrev_b64 v[216:217], 11, v[216:217]
	v_lshl_add_u64 v[216:217], v[168:169], 0, v[216:217]
	global_load_dwordx4 v[226:229], v[216:217], off
	global_load_dwordx4 v[230:233], v[216:217], off offset:256
	v_add_u32_e32 v216, 0xa0, v170
	v_ashrrev_i32_e32 v217, 31, v216
	v_lshlrev_b64 v[216:217], 11, v[216:217]
	v_lshl_add_u64 v[216:217], v[168:169], 0, v[216:217]
	global_load_dwordx4 v[234:237], v[216:217], off
	global_load_dwordx4 v[238:241], v[216:217], off offset:256
	v_add_u32_e32 v216, 0xb0, v170
	v_ashrrev_i32_e32 v217, 31, v216
	v_lshlrev_b64 v[216:217], 11, v[216:217]
	v_lshl_add_u64 v[216:217], v[168:169], 0, v[216:217]
	global_load_dwordx4 v[242:245], v[216:217], off
	global_load_dwordx4 v[246:249], v[216:217], off offset:256
	v_and_b32_e32 v199, 64, v219
	v_xor_b32_e32 v198, 16, v219
	v_add_u32_e32 v199, 64, v199
	v_cmp_lt_i32_e32 vcc, v198, v199
	v_xor_b32_e32 v208, 32, v219
	s_lshl_b32 s30, s16, 2
	v_cndmask_b32_e32 v198, v219, v198, vcc
	v_cmp_lt_i32_e32 vcc, v208, v199
	v_lshlrev_b32_e32 v198, 2, v198
	s_ashr_i32 s31, s30, 31
	v_cndmask_b32_e32 v199, v219, v208, vcc
	v_lshlrev_b32_e32 v199, 2, v199
	s_waitcnt vmcnt(0)
	v_lshlrev_b32_e32 v208, 16, v200
	v_and_b32_e32 v209, 0xffff0000, v200
	v_lshlrev_b32_e32 v200, 16, v201
	v_and_b32_e32 v201, 0xffff0000, v201
	v_lshlrev_b32_e32 v210, 16, v202
	v_and_b32_e32 v211, 0xffff0000, v202
	v_lshlrev_b32_e32 v202, 16, v203
	v_and_b32_e32 v203, 0xffff0000, v203
	v_pk_add_f32 v[200:201], v[122:123], v[200:201]
	v_pk_add_f32 v[208:209], v[120:121], v[208:209]
	v_pk_add_f32 v[126:127], v[126:127], v[202:203]
	v_pk_add_f32 v[124:125], v[124:125], v[210:211]
	v_lshl_add_u64 v[202:203], s[18:19], 0, v[206:207]
	v_cvt_pk_bf16_f32 v120, v208, v209
	v_cvt_pk_bf16_f32 v121, v200, v201
	v_cvt_pk_bf16_f32 v122, v124, v125
	v_cvt_pk_bf16_f32 v123, v126, v127
	v_lshl_add_u64 v[202:203], v[202:203], 0, v[204:205]
	global_store_dwordx4 v[202:203], v[120:123], off
	s_nop 1
	v_mul_f32_e32 v120, v209, v209
	v_mul_f32_e32 v121, v201, v201
	v_fmac_f32_e32 v120, v208, v208
	v_fmac_f32_e32 v121, v200, v200
	v_add_f32_e32 v120, v120, v121
	v_mul_f32_e32 v121, v125, v125
	v_mul_f32_e32 v122, v127, v127
	v_fmac_f32_e32 v121, v124, v124
	v_fmac_f32_e32 v122, v126, v126
	v_add_f32_e32 v121, v121, v122
	v_add_f32_e32 v200, v120, v121
	v_lshlrev_b32_e32 v120, 16, v152
	v_and_b32_e32 v121, 0xffff0000, v152
	v_lshlrev_b32_e32 v122, 16, v153
	v_and_b32_e32 v123, 0xffff0000, v153
	v_lshlrev_b32_e32 v124, 16, v154
	v_and_b32_e32 v125, 0xffff0000, v154
	v_lshlrev_b32_e32 v126, 16, v155
	v_and_b32_e32 v127, 0xffff0000, v155
	v_pk_add_f32 v[118:119], v[118:119], v[122:123]
	v_pk_add_f32 v[116:117], v[116:117], v[120:121]
	v_pk_add_f32 v[120:121], v[114:115], v[126:127]
	v_pk_add_f32 v[122:123], v[112:113], v[124:125]
	v_cvt_pk_bf16_f32 v112, v116, v117
	v_cvt_pk_bf16_f32 v113, v118, v119
	v_cvt_pk_bf16_f32 v114, v122, v123
	v_cvt_pk_bf16_f32 v115, v120, v121
	global_store_dwordx4 v[202:203], v[112:115], off offset:256
	s_nop 1
	v_mul_f32_e32 v112, v117, v117
	v_mul_f32_e32 v113, v119, v119
	v_fmac_f32_e32 v112, v116, v116
	v_fmac_f32_e32 v113, v118, v118
	v_add_f32_e32 v112, v112, v113
	v_mul_f32_e32 v113, v123, v123
	v_mul_f32_e32 v114, v121, v121
	v_fmac_f32_e32 v113, v122, v122
	v_fmac_f32_e32 v114, v120, v120
	v_add_f32_e32 v113, v113, v114
	v_add_f32_e32 v112, v112, v113
	v_add_f32_e32 v112, v200, v112
	ds_bpermute_b32 v113, v198, v112
	s_waitcnt lgkmcnt(0)
	v_add_f32_e32 v112, v112, v113
	ds_bpermute_b32 v113, v199, v112
	s_and_saveexec_b64 s[10:11], s[40:41]
	s_cbranch_execz .LBB0_267
	s_waitcnt lgkmcnt(0)
	v_add_f32_e32 v114, v112, v113
	v_lshlrev_b64 v[112:113], 6, v[170:171]
	v_lshl_add_u64 v[112:113], s[6:7], 0, v[112:113]
	v_lshl_add_u64 v[112:113], s[30:31], 2, v[112:113]
	s_lshl_b32 s16, s58, 2
	v_lshl_add_u64 v[112:113], v[112:113], 0, s[16:17]
	global_store_dword v[112:113], v114, off

.LBB0_273:
	s_or_b64 exec, exec, s[10:11]
	v_add_u32_e32 v104, 0x80, v170
	v_ashrrev_i32_e32 v105, 31, v104
	v_lshlrev_b64 v[110:111], 11, v[104:105]
	s_waitcnt lgkmcnt(0)
	v_lshl_add_u64 v[64:65], v[168:169], 0, v[110:111]
	v_add_u32_e32 v100, 0x90, v170
	v_ashrrev_i32_e32 v101, 31, v100
	v_add_u32_e32 v96, 0xa0, v170
	v_lshlrev_b64 v[102:103], 11, v[100:101]
	v_ashrrev_i32_e32 v97, 31, v96
	v_add_u32_e32 v92, 0xb0, v170
	v_lshl_add_u64 v[64:65], v[168:169], 0, v[102:103]
	v_lshlrev_b64 v[98:99], 11, v[96:97]
	v_ashrrev_i32_e32 v93, 31, v92
	v_lshl_add_u64 v[64:65], v[168:169], 0, v[98:99]
	v_lshlrev_b64 v[94:95], 11, v[92:93]
	v_lshl_add_u64 v[64:65], v[168:169], 0, v[94:95]
	s_nop 0
	v_lshl_add_u64 v[110:111], s[18:19], 0, v[110:111]
	v_lshl_add_u64 v[110:111], v[166:167], 1, v[110:111]
	v_lshlrev_b32_e32 v112, 16, v212
	v_and_b32_e32 v113, 0xffff0000, v212
	v_lshlrev_b32_e32 v106, 16, v213
	v_and_b32_e32 v107, 0xffff0000, v213
	v_lshlrev_b32_e32 v114, 16, v214
	v_and_b32_e32 v115, 0xffff0000, v214
	v_lshlrev_b32_e32 v108, 16, v215
	v_and_b32_e32 v109, 0xffff0000, v215
	v_pk_add_f32 v[62:63], v[62:63], v[106:107]
	v_pk_add_f32 v[60:61], v[60:61], v[112:113]
	v_pk_add_f32 v[106:107], v[58:59], v[108:109]
	v_pk_add_f32 v[108:109], v[56:57], v[114:115]
	v_cvt_pk_bf16_f32 v56, v60, v61
	v_cvt_pk_bf16_f32 v57, v62, v63
	v_cvt_pk_bf16_f32 v58, v108, v109
	v_cvt_pk_bf16_f32 v59, v106, v107
	global_store_dwordx4 v[110:111], v[56:59], off
	s_nop 1
	v_mul_f32_e32 v56, v61, v61
	v_mul_f32_e32 v57, v63, v63
	v_fmac_f32_e32 v56, v60, v60
	v_fmac_f32_e32 v57, v62, v62
	v_add_f32_e32 v56, v56, v57
	v_mul_f32_e32 v57, v109, v109
	v_mul_f32_e32 v58, v107, v107
	v_fmac_f32_e32 v57, v108, v108
	v_fmac_f32_e32 v58, v106, v106
	v_add_f32_e32 v57, v57, v58
	v_add_f32_e32 v106, v56, v57
	v_lshlrev_b32_e32 v56, 16, v222
	v_and_b32_e32 v57, 0xffff0000, v222
	v_lshlrev_b32_e32 v58, 16, v223
	v_and_b32_e32 v59, 0xffff0000, v223
	v_lshlrev_b32_e32 v60, 16, v224
	v_and_b32_e32 v61, 0xffff0000, v224
	v_lshlrev_b32_e32 v62, 16, v225
	v_and_b32_e32 v63, 0xffff0000, v225
	v_pk_add_f32 v[54:55], v[54:55], v[58:59]
	v_pk_add_f32 v[52:53], v[52:53], v[56:57]
	v_pk_add_f32 v[56:57], v[50:51], v[62:63]
	v_pk_add_f32 v[58:59], v[48:49], v[60:61]
	v_cvt_pk_bf16_f32 v48, v52, v53
	v_cvt_pk_bf16_f32 v49, v54, v55
	v_cvt_pk_bf16_f32 v50, v58, v59
	v_cvt_pk_bf16_f32 v51, v56, v57
	global_store_dwordx4 v[110:111], v[48:51], off offset:256
	s_nop 1
	v_mul_f32_e32 v48, v53, v53
	v_mul_f32_e32 v49, v55, v55
	v_fmac_f32_e32 v48, v52, v52
	v_fmac_f32_e32 v49, v54, v54
	v_add_f32_e32 v48, v48, v49
	v_mul_f32_e32 v49, v59, v59
	v_mul_f32_e32 v50, v57, v57
	v_fmac_f32_e32 v49, v58, v58
	v_fmac_f32_e32 v50, v56, v56
	v_add_f32_e32 v49, v49, v50
	v_add_f32_e32 v48, v48, v49
	v_add_f32_e32 v48, v106, v48
	ds_bpermute_b32 v49, v198, v48
	s_waitcnt lgkmcnt(0)
	v_add_f32_e32 v48, v48, v49
	ds_bpermute_b32 v49, v199, v48
	s_and_saveexec_b64 s[10:11], s[40:41]
	s_cbranch_execz .LBB0_275
	s_waitcnt lgkmcnt(0)
	v_add_f32_e32 v50, v48, v49
	v_lshlrev_b64 v[48:49], 6, v[104:105]
	v_lshl_add_u64 v[48:49], s[6:7], 0, v[48:49]
	v_lshl_add_u64 v[48:49], s[30:31], 2, v[48:49]
	s_lshl_b32 s16, s58, 2
	v_lshl_add_u64 v[48:49], v[48:49], 0, s[16:17]
	global_store_dword v[48:49], v50, off
.LBB0_275:
	s_or_b64 exec, exec, s[10:11]
	v_lshlrev_b32_e32 v48, 16, v226
	s_waitcnt lgkmcnt(0)
	v_and_b32_e32 v49, 0xffff0000, v226
	v_lshlrev_b32_e32 v50, 16, v227
	v_and_b32_e32 v51, 0xffff0000, v227
	v_lshlrev_b32_e32 v52, 16, v228
	v_and_b32_e32 v53, 0xffff0000, v228
	v_pk_add_f32 v[44:45], v[44:45], v[48:49]
	v_pk_add_f32 v[46:47], v[46:47], v[50:51]
	v_pk_add_f32 v[50:51], v[40:41], v[52:53]
	v_cvt_pk_bf16_f32 v40, v44, v45
	v_mul_f32_e32 v45, v45, v45
	v_lshlrev_b32_e32 v54, 16, v229
	v_and_b32_e32 v55, 0xffff0000, v229
	v_fmac_f32_e32 v45, v44, v44
	v_mul_f32_e32 v44, v47, v47
	v_pk_add_f32 v[48:49], v[42:43], v[54:55]
	v_fmac_f32_e32 v44, v46, v46
	v_cvt_pk_bf16_f32 v41, v46, v47
	v_add_f32_e32 v44, v45, v44
	v_mul_f32_e32 v45, v51, v51
	v_mul_f32_e32 v46, v49, v49
	v_fmac_f32_e32 v45, v50, v50
	v_fmac_f32_e32 v46, v48, v48
	v_add_f32_e32 v45, v45, v46
	v_add_f32_e32 v52, v44, v45
	v_lshlrev_b32_e32 v44, 16, v230
	v_and_b32_e32 v45, 0xffff0000, v230
	v_lshlrev_b32_e32 v46, 16, v231
	v_and_b32_e32 v47, 0xffff0000, v231
	v_cvt_pk_bf16_f32 v43, v48, v49
	v_lshlrev_b32_e32 v48, 16, v232
	v_and_b32_e32 v49, 0xffff0000, v232
	v_pk_add_f32 v[38:39], v[38:39], v[46:47]
	v_pk_add_f32 v[36:37], v[36:37], v[44:45]
	v_cvt_pk_bf16_f32 v42, v50, v51
	v_lshlrev_b32_e32 v50, 16, v233
	v_and_b32_e32 v51, 0xffff0000, v233
	v_pk_add_f32 v[46:47], v[32:33], v[48:49]
	v_mul_f32_e32 v32, v37, v37
	v_mul_f32_e32 v33, v39, v39
	v_pk_add_f32 v[44:45], v[34:35], v[50:51]
	v_fmac_f32_e32 v32, v36, v36
	v_fmac_f32_e32 v33, v38, v38
	v_add_f32_e32 v32, v32, v33
	v_mul_f32_e32 v33, v47, v47
	v_mul_f32_e32 v34, v45, v45
	v_fmac_f32_e32 v33, v46, v46
	v_fmac_f32_e32 v34, v44, v44
	v_add_f32_e32 v33, v33, v34
	v_add_f32_e32 v32, v32, v33
	v_add_f32_e32 v35, v52, v32
	ds_bpermute_b32 v50, v198, v35
	v_lshl_add_u64 v[32:33], s[18:19], 0, v[102:103]
	v_lshl_add_u64 v[48:49], v[166:167], 1, v[32:33]
	v_cvt_pk_bf16_f32 v34, v36, v37
	v_cvt_pk_bf16_f32 v36, v46, v47
	s_waitcnt lgkmcnt(0)
	v_add_f32_e32 v32, v35, v50
	ds_bpermute_b32 v33, v199, v32
	v_cvt_pk_bf16_f32 v35, v38, v39
	v_cvt_pk_bf16_f32 v37, v44, v45
	global_store_dwordx4 v[48:49], v[40:43], off
	global_store_dwordx4 v[48:49], v[34:37], off offset:256
	s_and_saveexec_b64 s[10:11], s[40:41]
	s_cbranch_execz .LBB0_277
	s_waitcnt lgkmcnt(0)
	v_add_f32_e32 v34, v32, v33
	v_lshlrev_b64 v[32:33], 6, v[100:101]
	v_lshl_add_u64 v[32:33], s[6:7], 0, v[32:33]
	v_lshl_add_u64 v[32:33], s[30:31], 2, v[32:33]
	s_lshl_b32 s16, s58, 2
	v_lshl_add_u64 v[32:33], v[32:33], 0, s[16:17]
	global_store_dword v[32:33], v34, off
.LBB0_277:
	s_or_b64 exec, exec, s[10:11]
	v_lshlrev_b32_e32 v32, 16, v234
	s_waitcnt lgkmcnt(0)
	v_and_b32_e32 v33, 0xffff0000, v234
	v_lshlrev_b32_e32 v34, 16, v235
	v_and_b32_e32 v35, 0xffff0000, v235
	v_lshlrev_b32_e32 v36, 16, v236
	v_and_b32_e32 v37, 0xffff0000, v236
	v_pk_add_f32 v[28:29], v[28:29], v[32:33]
	v_pk_add_f32 v[30:31], v[30:31], v[34:35]
	v_pk_add_f32 v[34:35], v[24:25], v[36:37]
	v_cvt_pk_bf16_f32 v24, v28, v29
	v_mul_f32_e32 v29, v29, v29
	v_lshlrev_b32_e32 v38, 16, v237
	v_and_b32_e32 v39, 0xffff0000, v237
	v_fmac_f32_e32 v29, v28, v28
	v_mul_f32_e32 v28, v31, v31
	v_pk_add_f32 v[32:33], v[26:27], v[38:39]
	v_fmac_f32_e32 v28, v30, v30
	v_cvt_pk_bf16_f32 v25, v30, v31
	v_add_f32_e32 v28, v29, v28
	v_mul_f32_e32 v29, v35, v35
	v_mul_f32_e32 v30, v33, v33
	v_fmac_f32_e32 v29, v34, v34
	v_fmac_f32_e32 v30, v32, v32
	v_add_f32_e32 v29, v29, v30
	v_add_f32_e32 v36, v28, v29
	v_lshlrev_b32_e32 v28, 16, v238
	v_and_b32_e32 v29, 0xffff0000, v238
	v_lshlrev_b32_e32 v30, 16, v239
	v_and_b32_e32 v31, 0xffff0000, v239
	v_cvt_pk_bf16_f32 v27, v32, v33
	v_lshlrev_b32_e32 v32, 16, v240
	v_and_b32_e32 v33, 0xffff0000, v240
	v_pk_add_f32 v[22:23], v[22:23], v[30:31]
	v_pk_add_f32 v[20:21], v[20:21], v[28:29]
	v_cvt_pk_bf16_f32 v26, v34, v35
	v_lshlrev_b32_e32 v34, 16, v241
	v_and_b32_e32 v35, 0xffff0000, v241
	v_pk_add_f32 v[30:31], v[16:17], v[32:33]
	v_mul_f32_e32 v16, v21, v21
	v_mul_f32_e32 v17, v23, v23
	v_pk_add_f32 v[28:29], v[18:19], v[34:35]
	v_fmac_f32_e32 v16, v20, v20
	v_fmac_f32_e32 v17, v22, v22
	v_add_f32_e32 v16, v16, v17
	v_mul_f32_e32 v17, v31, v31
	v_mul_f32_e32 v18, v29, v29
	v_fmac_f32_e32 v17, v30, v30
	v_fmac_f32_e32 v18, v28, v28
	v_add_f32_e32 v17, v17, v18
	v_add_f32_e32 v16, v16, v17
	v_add_f32_e32 v19, v36, v16
	ds_bpermute_b32 v34, v198, v19
	v_lshl_add_u64 v[16:17], s[18:19], 0, v[98:99]
	v_lshl_add_u64 v[32:33], v[166:167], 1, v[16:17]
	v_cvt_pk_bf16_f32 v18, v20, v21
	v_cvt_pk_bf16_f32 v20, v30, v31
	s_waitcnt lgkmcnt(0)
	v_add_f32_e32 v16, v19, v34
	ds_bpermute_b32 v17, v199, v16
	v_cvt_pk_bf16_f32 v19, v22, v23
	v_cvt_pk_bf16_f32 v21, v28, v29
	global_store_dwordx4 v[32:33], v[24:27], off
	global_store_dwordx4 v[32:33], v[18:21], off offset:256
	s_and_saveexec_b64 s[10:11], s[40:41]
	s_cbranch_execz .LBB0_279
	s_waitcnt lgkmcnt(0)
	v_add_f32_e32 v18, v16, v17
	v_lshlrev_b64 v[16:17], 6, v[96:97]
	v_lshl_add_u64 v[16:17], s[6:7], 0, v[16:17]
	v_lshl_add_u64 v[16:17], s[30:31], 2, v[16:17]
	s_lshl_b32 s16, s58, 2
	v_lshl_add_u64 v[16:17], v[16:17], 0, s[16:17]
	global_store_dword v[16:17], v18, off
.LBB0_279:
	s_or_b64 exec, exec, s[10:11]
	v_lshlrev_b32_e32 v16, 16, v242
	s_waitcnt lgkmcnt(0)
	v_and_b32_e32 v17, 0xffff0000, v242
	v_lshlrev_b32_e32 v18, 16, v243
	v_and_b32_e32 v19, 0xffff0000, v243
	v_lshlrev_b32_e32 v20, 16, v244
	v_and_b32_e32 v21, 0xffff0000, v244
	v_pk_add_f32 v[12:13], v[12:13], v[16:17]
	v_pk_add_f32 v[14:15], v[14:15], v[18:19]
	v_pk_add_f32 v[18:19], v[8:9], v[20:21]
	v_cvt_pk_bf16_f32 v8, v12, v13
	v_mul_f32_e32 v13, v13, v13
	v_lshlrev_b32_e32 v22, 16, v245
	v_and_b32_e32 v23, 0xffff0000, v245
	v_fmac_f32_e32 v13, v12, v12
	v_mul_f32_e32 v12, v15, v15
	v_pk_add_f32 v[16:17], v[10:11], v[22:23]
	v_fmac_f32_e32 v12, v14, v14
	v_cvt_pk_bf16_f32 v9, v14, v15
	v_add_f32_e32 v12, v13, v12
	v_mul_f32_e32 v13, v19, v19
	v_mul_f32_e32 v14, v17, v17
	v_fmac_f32_e32 v13, v18, v18
	v_fmac_f32_e32 v14, v16, v16
	v_add_f32_e32 v13, v13, v14
	v_add_f32_e32 v20, v12, v13
	v_lshlrev_b32_e32 v12, 16, v246
	v_and_b32_e32 v13, 0xffff0000, v246
	v_lshlrev_b32_e32 v14, 16, v247
	v_and_b32_e32 v15, 0xffff0000, v247
	v_cvt_pk_bf16_f32 v11, v16, v17
	v_lshlrev_b32_e32 v16, 16, v248
	v_and_b32_e32 v17, 0xffff0000, v248
	v_pk_add_f32 v[6:7], v[6:7], v[14:15]
	v_pk_add_f32 v[4:5], v[4:5], v[12:13]
	v_cvt_pk_bf16_f32 v10, v18, v19
	v_lshlrev_b32_e32 v18, 16, v249
	v_and_b32_e32 v19, 0xffff0000, v249
	v_pk_add_f32 v[14:15], v[0:1], v[16:17]
	v_mul_f32_e32 v0, v5, v5
	v_mul_f32_e32 v1, v7, v7
	v_pk_add_f32 v[12:13], v[2:3], v[18:19]
	v_fmac_f32_e32 v0, v4, v4
	v_fmac_f32_e32 v1, v6, v6
	v_add_f32_e32 v0, v0, v1
	v_mul_f32_e32 v1, v15, v15
	v_mul_f32_e32 v2, v13, v13
	v_fmac_f32_e32 v1, v14, v14
	v_fmac_f32_e32 v2, v12, v12
	v_add_f32_e32 v1, v1, v2
	v_add_f32_e32 v0, v0, v1
	v_add_f32_e32 v3, v20, v0
	ds_bpermute_b32 v18, v198, v3
	v_lshl_add_u64 v[0:1], s[18:19], 0, v[94:95]
	v_lshl_add_u64 v[16:17], v[166:167], 1, v[0:1]
	v_cvt_pk_bf16_f32 v2, v4, v5
	v_cvt_pk_bf16_f32 v4, v14, v15
	s_waitcnt lgkmcnt(0)
	v_add_f32_e32 v0, v3, v18
	ds_bpermute_b32 v1, v199, v0
	v_cvt_pk_bf16_f32 v3, v6, v7
	v_cvt_pk_bf16_f32 v5, v12, v13
	global_store_dwordx4 v[16:17], v[8:11], off
	global_store_dwordx4 v[16:17], v[2:5], off offset:256
	s_and_saveexec_b64 s[10:11], s[40:41]
	s_cbranch_execz .LBB0_281
	s_waitcnt lgkmcnt(0)
	v_add_f32_e32 v2, v0, v1
	v_lshlrev_b64 v[0:1], 6, v[92:93]
	v_lshl_add_u64 v[0:1], s[6:7], 0, v[0:1]
	v_lshl_add_u64 v[0:1], s[30:31], 2, v[0:1]
	s_lshl_b32 s16, s58, 2
	v_lshl_add_u64 v[0:1], v[0:1], 0, s[16:17]
	global_store_dword v[0:1], v2, off

.LBB0_478:
	v_lshl_or_b32 v166, s16, 8, v196
	v_lshl_add_u32 v170, s67, 8, v194
	v_ashrrev_i32_e32 v167, 31, v166
	v_lshlrev_b64 v[204:205], 1, v[166:167]
	v_ashrrev_i32_e32 v171, 31, v170
	v_lshl_add_u64 v[168:169], s[18:19], 0, v[204:205]
	v_lshlrev_b64 v[206:207], 11, v[170:171]
	v_lshl_add_u64 v[128:129], v[168:169], 0, v[206:207]
	global_load_dwordx4 v[200:203], v[128:129], off
	global_load_dwordx4 v[152:155], v[128:129], off offset:256
	v_or_b32_e32 v190, 16, v170
	v_ashrrev_i32_e32 v191, 31, v190
	v_or_b32_e32 v186, 32, v170
	v_lshlrev_b64 v[192:193], 11, v[190:191]
	v_ashrrev_i32_e32 v187, 31, v186
	v_or_b32_e32 v172, 48, v170
	v_lshl_add_u64 v[128:129], v[168:169], 0, v[192:193]
	v_lshlrev_b64 v[188:189], 11, v[186:187]
	v_ashrrev_i32_e32 v173, 31, v172
	global_load_dwordx4 v[148:151], v[128:129], off
	global_load_dwordx4 v[144:147], v[128:129], off offset:256
	v_lshl_add_u64 v[128:129], v[168:169], 0, v[188:189]
	v_lshlrev_b64 v[174:175], 11, v[172:173]
	global_load_dwordx4 v[140:143], v[128:129], off
	global_load_dwordx4 v[136:139], v[128:129], off offset:256
	v_lshl_add_u64 v[128:129], v[168:169], 0, v[174:175]
	global_load_dwordx4 v[132:135], v[128:129], off
	s_nop 0
	global_load_dwordx4 v[128:131], v[128:129], off offset:256
	v_add_u32_e32 v216, 0x80, v170
	v_ashrrev_i32_e32 v217, 31, v216
	v_lshlrev_b64 v[216:217], 11, v[216:217]
	v_lshl_add_u64 v[216:217], v[168:169], 0, v[216:217]
	global_load_dwordx4 v[212:215], v[216:217], off
	global_load_dwordx4 v[222:225], v[216:217], off offset:256
	v_add_u32_e32 v216, 0x90, v170
	v_ashrrev_i32_e32 v217, 31, v216
	v_lshlrev_b64 v[216:217], 11, v[216:217]
	v_lshl_add_u64 v[216:217], v[168:169], 0, v[216:217]
	global_load_dwordx4 v[226:229], v[216:217], off
	global_load_dwordx4 v[230:233], v[216:217], off offset:256
	v_add_u32_e32 v216, 0xa0, v170
	v_ashrrev_i32_e32 v217, 31, v216
	v_lshlrev_b64 v[216:217], 11, v[216:217]
	v_lshl_add_u64 v[216:217], v[168:169], 0, v[216:217]
	global_load_dwordx4 v[234:237], v[216:217], off
	global_load_dwordx4 v[238:241], v[216:217], off offset:256
	v_add_u32_e32 v216, 0xb0, v170
	v_ashrrev_i32_e32 v217, 31, v216
	v_lshlrev_b64 v[216:217], 11, v[216:217]
	v_lshl_add_u64 v[216:217], v[168:169], 0, v[216:217]
	global_load_dwordx4 v[242:245], v[216:217], off
	global_load_dwordx4 v[246:249], v[216:217], off offset:256
	v_and_b32_e32 v199, 64, v219
	v_xor_b32_e32 v198, 16, v219
	v_add_u32_e32 v199, 64, v199
	v_cmp_lt_i32_e32 vcc, v198, v199
	v_xor_b32_e32 v208, 32, v219
	s_lshl_b32 s28, s16, 2
	v_cndmask_b32_e32 v198, v219, v198, vcc
	v_cmp_lt_i32_e32 vcc, v208, v199
	v_lshlrev_b32_e32 v198, 2, v198
	s_ashr_i32 s29, s28, 31
	v_cndmask_b32_e32 v199, v219, v208, vcc
	v_lshlrev_b32_e32 v199, 2, v199
	s_waitcnt vmcnt(0)
	v_lshlrev_b32_e32 v208, 16, v200
	v_and_b32_e32 v209, 0xffff0000, v200
	v_lshlrev_b32_e32 v200, 16, v201
	v_and_b32_e32 v201, 0xffff0000, v201
	v_lshlrev_b32_e32 v210, 16, v202
	v_and_b32_e32 v211, 0xffff0000, v202
	v_lshlrev_b32_e32 v202, 16, v203
	v_and_b32_e32 v203, 0xffff0000, v203
	v_pk_add_f32 v[200:201], v[122:123], v[200:201]
	v_pk_add_f32 v[208:209], v[120:121], v[208:209]
	v_pk_add_f32 v[126:127], v[126:127], v[202:203]
	v_pk_add_f32 v[124:125], v[124:125], v[210:211]
	v_lshl_add_u64 v[202:203], s[18:19], 0, v[206:207]
	v_cvt_pk_bf16_f32 v120, v208, v209
	v_cvt_pk_bf16_f32 v121, v200, v201
	v_cvt_pk_bf16_f32 v122, v124, v125
	v_cvt_pk_bf16_f32 v123, v126, v127
	v_lshl_add_u64 v[202:203], v[202:203], 0, v[204:205]
	global_store_dwordx4 v[202:203], v[120:123], off
	s_nop 1
	v_mul_f32_e32 v120, v209, v209
	v_mul_f32_e32 v121, v201, v201
	v_fmac_f32_e32 v120, v208, v208
	v_fmac_f32_e32 v121, v200, v200
	v_add_f32_e32 v120, v120, v121
	v_mul_f32_e32 v121, v125, v125
	v_mul_f32_e32 v122, v127, v127
	v_fmac_f32_e32 v121, v124, v124
	v_fmac_f32_e32 v122, v126, v126
	v_add_f32_e32 v121, v121, v122
	v_add_f32_e32 v200, v120, v121
	v_lshlrev_b32_e32 v120, 16, v152
	v_and_b32_e32 v121, 0xffff0000, v152
	v_lshlrev_b32_e32 v122, 16, v153
	v_and_b32_e32 v123, 0xffff0000, v153
	v_lshlrev_b32_e32 v124, 16, v154
	v_and_b32_e32 v125, 0xffff0000, v154
	v_lshlrev_b32_e32 v126, 16, v155
	v_and_b32_e32 v127, 0xffff0000, v155
	v_pk_add_f32 v[118:119], v[118:119], v[122:123]
	v_pk_add_f32 v[116:117], v[116:117], v[120:121]
	v_pk_add_f32 v[120:121], v[114:115], v[126:127]
	v_pk_add_f32 v[122:123], v[112:113], v[124:125]
	v_cvt_pk_bf16_f32 v112, v116, v117
	v_cvt_pk_bf16_f32 v113, v118, v119
	v_cvt_pk_bf16_f32 v114, v122, v123
	v_cvt_pk_bf16_f32 v115, v120, v121
	global_store_dwordx4 v[202:203], v[112:115], off offset:256
	s_nop 1
	v_mul_f32_e32 v112, v117, v117
	v_mul_f32_e32 v113, v119, v119
	v_fmac_f32_e32 v112, v116, v116
	v_fmac_f32_e32 v113, v118, v118
	v_add_f32_e32 v112, v112, v113
	v_mul_f32_e32 v113, v123, v123
	v_mul_f32_e32 v114, v121, v121
	v_fmac_f32_e32 v113, v122, v122
	v_fmac_f32_e32 v114, v120, v120
	v_add_f32_e32 v113, v113, v114
	v_add_f32_e32 v112, v112, v113
	v_add_f32_e32 v112, v200, v112
	ds_bpermute_b32 v113, v198, v112
	s_waitcnt lgkmcnt(0)
	v_add_f32_e32 v112, v112, v113
	ds_bpermute_b32 v113, v199, v112
	s_and_saveexec_b64 s[10:11], s[40:41]
	s_cbranch_execz .LBB0_480
	s_waitcnt lgkmcnt(0)
	v_add_f32_e32 v114, v112, v113
	v_lshlrev_b64 v[112:113], 6, v[170:171]
	v_lshl_add_u64 v[112:113], s[0:1], 0, v[112:113]
	v_lshl_add_u64 v[112:113], s[28:29], 2, v[112:113]
	s_lshl_b32 s16, s51, 2
	v_lshl_add_u64 v[112:113], v[112:113], 0, s[16:17]
	global_store_dword v[112:113], v114, off

.LBB0_486:
	s_or_b64 exec, exec, s[10:11]
	v_add_u32_e32 v104, 0x80, v170
	v_ashrrev_i32_e32 v105, 31, v104
	v_lshlrev_b64 v[110:111], 11, v[104:105]
	s_waitcnt lgkmcnt(0)
	v_lshl_add_u64 v[64:65], v[168:169], 0, v[110:111]
	v_add_u32_e32 v100, 0x90, v170
	v_ashrrev_i32_e32 v101, 31, v100
	v_add_u32_e32 v96, 0xa0, v170
	v_lshlrev_b64 v[102:103], 11, v[100:101]
	v_ashrrev_i32_e32 v97, 31, v96
	v_add_u32_e32 v92, 0xb0, v170
	v_lshl_add_u64 v[64:65], v[168:169], 0, v[102:103]
	v_lshlrev_b64 v[98:99], 11, v[96:97]
	v_ashrrev_i32_e32 v93, 31, v92
	v_lshl_add_u64 v[64:65], v[168:169], 0, v[98:99]
	v_lshlrev_b64 v[94:95], 11, v[92:93]
	v_lshl_add_u64 v[64:65], v[168:169], 0, v[94:95]
	s_nop 0
	v_lshl_add_u64 v[110:111], s[18:19], 0, v[110:111]
	v_lshl_add_u64 v[110:111], v[166:167], 1, v[110:111]
	v_lshlrev_b32_e32 v112, 16, v212
	v_and_b32_e32 v113, 0xffff0000, v212
	v_lshlrev_b32_e32 v106, 16, v213
	v_and_b32_e32 v107, 0xffff0000, v213
	v_lshlrev_b32_e32 v114, 16, v214
	v_and_b32_e32 v115, 0xffff0000, v214
	v_lshlrev_b32_e32 v108, 16, v215
	v_and_b32_e32 v109, 0xffff0000, v215
	v_pk_add_f32 v[62:63], v[62:63], v[106:107]
	v_pk_add_f32 v[60:61], v[60:61], v[112:113]
	v_pk_add_f32 v[106:107], v[58:59], v[108:109]
	v_pk_add_f32 v[108:109], v[56:57], v[114:115]
	v_cvt_pk_bf16_f32 v56, v60, v61
	v_cvt_pk_bf16_f32 v57, v62, v63
	v_cvt_pk_bf16_f32 v58, v108, v109
	v_cvt_pk_bf16_f32 v59, v106, v107
	global_store_dwordx4 v[110:111], v[56:59], off
	s_nop 1
	v_mul_f32_e32 v56, v61, v61
	v_mul_f32_e32 v57, v63, v63
	v_fmac_f32_e32 v56, v60, v60
	v_fmac_f32_e32 v57, v62, v62
	v_add_f32_e32 v56, v56, v57
	v_mul_f32_e32 v57, v109, v109
	v_mul_f32_e32 v58, v107, v107
	v_fmac_f32_e32 v57, v108, v108
	v_fmac_f32_e32 v58, v106, v106
	v_add_f32_e32 v57, v57, v58
	v_add_f32_e32 v106, v56, v57
	v_lshlrev_b32_e32 v56, 16, v222
	v_and_b32_e32 v57, 0xffff0000, v222
	v_lshlrev_b32_e32 v58, 16, v223
	v_and_b32_e32 v59, 0xffff0000, v223
	v_lshlrev_b32_e32 v60, 16, v224
	v_and_b32_e32 v61, 0xffff0000, v224
	v_lshlrev_b32_e32 v62, 16, v225
	v_and_b32_e32 v63, 0xffff0000, v225
	v_pk_add_f32 v[54:55], v[54:55], v[58:59]
	v_pk_add_f32 v[52:53], v[52:53], v[56:57]
	v_pk_add_f32 v[56:57], v[50:51], v[62:63]
	v_pk_add_f32 v[58:59], v[48:49], v[60:61]
	v_cvt_pk_bf16_f32 v48, v52, v53
	v_cvt_pk_bf16_f32 v49, v54, v55
	v_cvt_pk_bf16_f32 v50, v58, v59
	v_cvt_pk_bf16_f32 v51, v56, v57
	global_store_dwordx4 v[110:111], v[48:51], off offset:256
	s_nop 1
	v_mul_f32_e32 v48, v53, v53
	v_mul_f32_e32 v49, v55, v55
	v_fmac_f32_e32 v48, v52, v52
	v_fmac_f32_e32 v49, v54, v54
	v_add_f32_e32 v48, v48, v49
	v_mul_f32_e32 v49, v59, v59
	v_mul_f32_e32 v50, v57, v57
	v_fmac_f32_e32 v49, v58, v58
	v_fmac_f32_e32 v50, v56, v56
	v_add_f32_e32 v49, v49, v50
	v_add_f32_e32 v48, v48, v49
	v_add_f32_e32 v48, v106, v48
	ds_bpermute_b32 v49, v198, v48
	s_waitcnt lgkmcnt(0)
	v_add_f32_e32 v48, v48, v49
	ds_bpermute_b32 v49, v199, v48
	s_and_saveexec_b64 s[10:11], s[40:41]
	s_cbranch_execz .LBB0_488
	s_waitcnt lgkmcnt(0)
	v_add_f32_e32 v50, v48, v49
	v_lshlrev_b64 v[48:49], 6, v[104:105]
	v_lshl_add_u64 v[48:49], s[0:1], 0, v[48:49]
	v_lshl_add_u64 v[48:49], s[28:29], 2, v[48:49]
	s_lshl_b32 s16, s51, 2
	v_lshl_add_u64 v[48:49], v[48:49], 0, s[16:17]
	global_store_dword v[48:49], v50, off
.LBB0_488:
	s_or_b64 exec, exec, s[10:11]
	v_lshlrev_b32_e32 v48, 16, v226
	s_waitcnt lgkmcnt(0)
	v_and_b32_e32 v49, 0xffff0000, v226
	v_lshlrev_b32_e32 v50, 16, v227
	v_and_b32_e32 v51, 0xffff0000, v227
	v_lshlrev_b32_e32 v52, 16, v228
	v_and_b32_e32 v53, 0xffff0000, v228
	v_pk_add_f32 v[44:45], v[44:45], v[48:49]
	v_pk_add_f32 v[46:47], v[46:47], v[50:51]
	v_pk_add_f32 v[50:51], v[40:41], v[52:53]
	v_cvt_pk_bf16_f32 v40, v44, v45
	v_mul_f32_e32 v45, v45, v45
	v_lshlrev_b32_e32 v54, 16, v229
	v_and_b32_e32 v55, 0xffff0000, v229
	v_fmac_f32_e32 v45, v44, v44
	v_mul_f32_e32 v44, v47, v47
	v_pk_add_f32 v[48:49], v[42:43], v[54:55]
	v_fmac_f32_e32 v44, v46, v46
	v_cvt_pk_bf16_f32 v41, v46, v47
	v_add_f32_e32 v44, v45, v44
	v_mul_f32_e32 v45, v51, v51
	v_mul_f32_e32 v46, v49, v49
	v_fmac_f32_e32 v45, v50, v50
	v_fmac_f32_e32 v46, v48, v48
	v_add_f32_e32 v45, v45, v46
	v_add_f32_e32 v52, v44, v45
	v_lshlrev_b32_e32 v44, 16, v230
	v_and_b32_e32 v45, 0xffff0000, v230
	v_lshlrev_b32_e32 v46, 16, v231
	v_and_b32_e32 v47, 0xffff0000, v231
	v_cvt_pk_bf16_f32 v43, v48, v49
	v_lshlrev_b32_e32 v48, 16, v232
	v_and_b32_e32 v49, 0xffff0000, v232
	v_pk_add_f32 v[38:39], v[38:39], v[46:47]
	v_pk_add_f32 v[36:37], v[36:37], v[44:45]
	v_cvt_pk_bf16_f32 v42, v50, v51
	v_lshlrev_b32_e32 v50, 16, v233
	v_and_b32_e32 v51, 0xffff0000, v233
	v_pk_add_f32 v[46:47], v[32:33], v[48:49]
	v_mul_f32_e32 v32, v37, v37
	v_mul_f32_e32 v33, v39, v39
	v_pk_add_f32 v[44:45], v[34:35], v[50:51]
	v_fmac_f32_e32 v32, v36, v36
	v_fmac_f32_e32 v33, v38, v38
	v_add_f32_e32 v32, v32, v33
	v_mul_f32_e32 v33, v47, v47
	v_mul_f32_e32 v34, v45, v45
	v_fmac_f32_e32 v33, v46, v46
	v_fmac_f32_e32 v34, v44, v44
	v_add_f32_e32 v33, v33, v34
	v_add_f32_e32 v32, v32, v33
	v_add_f32_e32 v35, v52, v32
	ds_bpermute_b32 v50, v198, v35
	v_lshl_add_u64 v[32:33], s[18:19], 0, v[102:103]
	v_lshl_add_u64 v[48:49], v[166:167], 1, v[32:33]
	v_cvt_pk_bf16_f32 v34, v36, v37
	v_cvt_pk_bf16_f32 v36, v46, v47
	s_waitcnt lgkmcnt(0)
	v_add_f32_e32 v32, v35, v50
	ds_bpermute_b32 v33, v199, v32
	v_cvt_pk_bf16_f32 v35, v38, v39
	v_cvt_pk_bf16_f32 v37, v44, v45
	global_store_dwordx4 v[48:49], v[40:43], off
	global_store_dwordx4 v[48:49], v[34:37], off offset:256
	s_and_saveexec_b64 s[10:11], s[40:41]
	s_cbranch_execz .LBB0_490
	s_waitcnt lgkmcnt(0)
	v_add_f32_e32 v34, v32, v33
	v_lshlrev_b64 v[32:33], 6, v[100:101]
	v_lshl_add_u64 v[32:33], s[0:1], 0, v[32:33]
	v_lshl_add_u64 v[32:33], s[28:29], 2, v[32:33]
	s_lshl_b32 s16, s51, 2
	v_lshl_add_u64 v[32:33], v[32:33], 0, s[16:17]
	global_store_dword v[32:33], v34, off
.LBB0_490:
	s_or_b64 exec, exec, s[10:11]
	v_lshlrev_b32_e32 v32, 16, v234
	s_waitcnt lgkmcnt(0)
	v_and_b32_e32 v33, 0xffff0000, v234
	v_lshlrev_b32_e32 v34, 16, v235
	v_and_b32_e32 v35, 0xffff0000, v235
	v_lshlrev_b32_e32 v36, 16, v236
	v_and_b32_e32 v37, 0xffff0000, v236
	v_pk_add_f32 v[28:29], v[28:29], v[32:33]
	v_pk_add_f32 v[30:31], v[30:31], v[34:35]
	v_pk_add_f32 v[34:35], v[24:25], v[36:37]
	v_cvt_pk_bf16_f32 v24, v28, v29
	v_mul_f32_e32 v29, v29, v29
	v_lshlrev_b32_e32 v38, 16, v237
	v_and_b32_e32 v39, 0xffff0000, v237
	v_fmac_f32_e32 v29, v28, v28
	v_mul_f32_e32 v28, v31, v31
	v_pk_add_f32 v[32:33], v[26:27], v[38:39]
	v_fmac_f32_e32 v28, v30, v30
	v_cvt_pk_bf16_f32 v25, v30, v31
	v_add_f32_e32 v28, v29, v28
	v_mul_f32_e32 v29, v35, v35
	v_mul_f32_e32 v30, v33, v33
	v_fmac_f32_e32 v29, v34, v34
	v_fmac_f32_e32 v30, v32, v32
	v_add_f32_e32 v29, v29, v30
	v_add_f32_e32 v36, v28, v29
	v_lshlrev_b32_e32 v28, 16, v238
	v_and_b32_e32 v29, 0xffff0000, v238
	v_lshlrev_b32_e32 v30, 16, v239
	v_and_b32_e32 v31, 0xffff0000, v239
	v_cvt_pk_bf16_f32 v27, v32, v33
	v_lshlrev_b32_e32 v32, 16, v240
	v_and_b32_e32 v33, 0xffff0000, v240
	v_pk_add_f32 v[22:23], v[22:23], v[30:31]
	v_pk_add_f32 v[20:21], v[20:21], v[28:29]
	v_cvt_pk_bf16_f32 v26, v34, v35
	v_lshlrev_b32_e32 v34, 16, v241
	v_and_b32_e32 v35, 0xffff0000, v241
	v_pk_add_f32 v[30:31], v[16:17], v[32:33]
	v_mul_f32_e32 v16, v21, v21
	v_mul_f32_e32 v17, v23, v23
	v_pk_add_f32 v[28:29], v[18:19], v[34:35]
	v_fmac_f32_e32 v16, v20, v20
	v_fmac_f32_e32 v17, v22, v22
	v_add_f32_e32 v16, v16, v17
	v_mul_f32_e32 v17, v31, v31
	v_mul_f32_e32 v18, v29, v29
	v_fmac_f32_e32 v17, v30, v30
	v_fmac_f32_e32 v18, v28, v28
	v_add_f32_e32 v17, v17, v18
	v_add_f32_e32 v16, v16, v17
	v_add_f32_e32 v19, v36, v16
	ds_bpermute_b32 v34, v198, v19
	v_lshl_add_u64 v[16:17], s[18:19], 0, v[98:99]
	v_lshl_add_u64 v[32:33], v[166:167], 1, v[16:17]
	v_cvt_pk_bf16_f32 v18, v20, v21
	v_cvt_pk_bf16_f32 v20, v30, v31
	s_waitcnt lgkmcnt(0)
	v_add_f32_e32 v16, v19, v34
	ds_bpermute_b32 v17, v199, v16
	v_cvt_pk_bf16_f32 v19, v22, v23
	v_cvt_pk_bf16_f32 v21, v28, v29
	global_store_dwordx4 v[32:33], v[24:27], off
	global_store_dwordx4 v[32:33], v[18:21], off offset:256
	s_and_saveexec_b64 s[10:11], s[40:41]
	s_cbranch_execz .LBB0_492
	s_waitcnt lgkmcnt(0)
	v_add_f32_e32 v18, v16, v17
	v_lshlrev_b64 v[16:17], 6, v[96:97]
	v_lshl_add_u64 v[16:17], s[0:1], 0, v[16:17]
	v_lshl_add_u64 v[16:17], s[28:29], 2, v[16:17]
	s_lshl_b32 s16, s51, 2
	v_lshl_add_u64 v[16:17], v[16:17], 0, s[16:17]
	global_store_dword v[16:17], v18, off
.LBB0_492:
	s_or_b64 exec, exec, s[10:11]
	v_lshlrev_b32_e32 v16, 16, v242
	s_waitcnt lgkmcnt(0)
	v_and_b32_e32 v17, 0xffff0000, v242
	v_lshlrev_b32_e32 v18, 16, v243
	v_and_b32_e32 v19, 0xffff0000, v243
	v_lshlrev_b32_e32 v20, 16, v244
	v_and_b32_e32 v21, 0xffff0000, v244
	v_pk_add_f32 v[12:13], v[12:13], v[16:17]
	v_pk_add_f32 v[14:15], v[14:15], v[18:19]
	v_pk_add_f32 v[18:19], v[8:9], v[20:21]
	v_cvt_pk_bf16_f32 v8, v12, v13
	v_mul_f32_e32 v13, v13, v13
	v_lshlrev_b32_e32 v22, 16, v245
	v_and_b32_e32 v23, 0xffff0000, v245
	v_fmac_f32_e32 v13, v12, v12
	v_mul_f32_e32 v12, v15, v15
	v_pk_add_f32 v[16:17], v[10:11], v[22:23]
	v_fmac_f32_e32 v12, v14, v14
	v_cvt_pk_bf16_f32 v9, v14, v15
	v_add_f32_e32 v12, v13, v12
	v_mul_f32_e32 v13, v19, v19
	v_mul_f32_e32 v14, v17, v17
	v_fmac_f32_e32 v13, v18, v18
	v_fmac_f32_e32 v14, v16, v16
	v_add_f32_e32 v13, v13, v14
	v_add_f32_e32 v20, v12, v13
	v_lshlrev_b32_e32 v12, 16, v246
	v_and_b32_e32 v13, 0xffff0000, v246
	v_lshlrev_b32_e32 v14, 16, v247
	v_and_b32_e32 v15, 0xffff0000, v247
	v_cvt_pk_bf16_f32 v11, v16, v17
	v_lshlrev_b32_e32 v16, 16, v248
	v_and_b32_e32 v17, 0xffff0000, v248
	v_pk_add_f32 v[6:7], v[6:7], v[14:15]
	v_pk_add_f32 v[4:5], v[4:5], v[12:13]
	v_cvt_pk_bf16_f32 v10, v18, v19
	v_lshlrev_b32_e32 v18, 16, v249
	v_and_b32_e32 v19, 0xffff0000, v249
	v_pk_add_f32 v[14:15], v[0:1], v[16:17]
	v_mul_f32_e32 v0, v5, v5
	v_mul_f32_e32 v1, v7, v7
	v_pk_add_f32 v[12:13], v[2:3], v[18:19]
	v_fmac_f32_e32 v0, v4, v4
	v_fmac_f32_e32 v1, v6, v6
	v_add_f32_e32 v0, v0, v1
	v_mul_f32_e32 v1, v15, v15
	v_mul_f32_e32 v2, v13, v13
	v_fmac_f32_e32 v1, v14, v14
	v_fmac_f32_e32 v2, v12, v12
	v_add_f32_e32 v1, v1, v2
	v_add_f32_e32 v0, v0, v1
	v_add_f32_e32 v3, v20, v0
	ds_bpermute_b32 v18, v198, v3
	v_lshl_add_u64 v[0:1], s[18:19], 0, v[94:95]
	v_lshl_add_u64 v[16:17], v[166:167], 1, v[0:1]
	v_cvt_pk_bf16_f32 v2, v4, v5
	v_cvt_pk_bf16_f32 v4, v14, v15
	s_waitcnt lgkmcnt(0)
	v_add_f32_e32 v0, v3, v18
	ds_bpermute_b32 v1, v199, v0
	v_cvt_pk_bf16_f32 v3, v6, v7
	v_cvt_pk_bf16_f32 v5, v12, v13
	global_store_dwordx4 v[16:17], v[8:11], off
	global_store_dwordx4 v[16:17], v[2:5], off offset:256
	s_and_saveexec_b64 s[10:11], s[40:41]
	s_cbranch_execz .LBB0_494
	s_waitcnt lgkmcnt(0)
	v_add_f32_e32 v2, v0, v1
	v_lshlrev_b64 v[0:1], 6, v[92:93]
	v_lshl_add_u64 v[0:1], s[0:1], 0, v[0:1]
	v_lshl_add_u64 v[0:1], s[28:29], 2, v[0:1]
	s_lshl_b32 s16, s51, 2
	v_lshl_add_u64 v[0:1], v[0:1], 0, s[16:17]
	global_store_dword v[0:1], v2, off
